# P1G: P1 gates epilogue loads both b_gate vectors once (v[238:253]) instead of 16 reloads each waited behind the previous store
# speedup vs baseline: 1.0115x; 1.0115x over previous
; __device__ __forceinline__ float fast_sigmoid(float z) { return __builtin_amdgcn_rcpf(1.f + __builtin_amdgcn_exp2f(-z * L2E)); }
; __device__ __forceinline__ u32x4 pack8(f32x4 a, f32x4 b) { u32x4 w; w.x = cvt_pk_bf16(a[0], a[1]); w.y = cvt_pk_bf16(a[2], a[3]); w.z = cvt_pk_bf16(b[0], b[1]); w.w = cvt_pk_bf16(b[2], b[3]); return w; }
; #define EPI_LOOP(...) _Pragma("unroll") for (int ai = 0; ai < 2; ++ai) _Pragma("unroll") for (int m = 0; m < 4; ++m) { const int row = u.pm * 256 + ai * 128 + wr * 64 + m * 16 + fr; \
;     _Pragma("unroll") for (int bj = 0; bj < 2; ++bj) { const int tc = bj * 128 + wc * 32 + 8 * fq; f32x4 v0 = acc[ai][bj][m][0], v1 = acc[ai][bj][m][1]; __VA_ARGS__ } }
;     __device__ __forceinline__ void operator()(const f32x4 (&acc)[2][2][4][2], const pg8::Unit& u, int wr, int wc, int fr, int fq) const {
;     ...
;             const int gt = (u.pn - 20) * 256;
;             EPI_LOOP({ const int col = gt + tc; const f32x4 b0 = *(const f32x4*)(b_gate + col), b1 = *(const f32x4*)(b_gate + col + 4);
;                        _Pragma("unroll") for (int i = 0; i < 4; ++i) { v0[i] = fast_sigmoid(v0[i] + b0[i]); v1[i] = fast_sigmoid(v1[i] + b1[i]); }
;                        *(u32x4*)(G + (size_t)row * 2048 + col) = pack8(v0, v1); })
.LBB0_256:
	s_add_i32 s28, s23, -3
	s_cmp_gt_u32 s28, 1
	s_mov_b64 s[28:29], -1
	s_cbranch_scc0 .LBB0_258
	v_add_u32_e32 v156, s1, v161
	v_ashrrev_i32_e32 v157, 31, v156
	v_lshl_add_u64 v[152:153], v[156:157], 2, s[72:73]
	global_load_dwordx4 v[238:241], v[152:153], off
	global_load_dwordx4 v[242:245], v[152:153], off offset:16
	global_load_dwordx4 v[246:249], v[152:153], off offset:512
	global_load_dwordx4 v[250:253], v[152:153], off offset:528
	v_lshl_add_u32 v154, s0, 8, v129
	v_ashrrev_i32_e32 v155, 31, v154
	v_lshlrev_b64 v[158:159], 12, v[154:155]
	v_lshlrev_b64 v[156:157], 1, v[156:157]
	v_lshl_add_u64 v[158:159], s[12:13], 0, v[158:159]
	v_lshl_add_u64 v[158:159], v[158:159], 0, v[156:157]
	s_mov_b64 s[28:29], 0
	s_waitcnt vmcnt(0)
	v_add_f32_e32 v142, v124, v238
	v_add_f32_e32 v155, v120, v242
	v_add_f32_e32 v172, v125, v239
	v_add_f32_e32 v173, v121, v243
	v_add_f32_e32 v174, v126, v240
	v_add_f32_e32 v176, v122, v244
	v_add_f32_e32 v175, v127, v241
	v_add_f32_e32 v177, v123, v245
	v_mul_f32_e32 v172, 0xbfb8aa3b, v172
	v_mul_f32_e32 v173, 0xbfb8aa3b, v173
	v_mul_f32_e32 v174, 0xbfb8aa3b, v174
	v_mul_f32_e32 v176, 0xbfb8aa3b, v176
	v_mul_f32_e32 v175, 0xbfb8aa3b, v175
	v_mul_f32_e32 v142, 0xbfb8aa3b, v142
	v_mul_f32_e32 v155, 0xbfb8aa3b, v155
	v_mul_f32_e32 v177, 0xbfb8aa3b, v177
	v_exp_f32_e32 v172, v172
	v_exp_f32_e32 v173, v173
	v_exp_f32_e32 v174, v174
	v_exp_f32_e32 v176, v176
	v_exp_f32_e32 v175, v175
	v_exp_f32_e32 v142, v142
	v_exp_f32_e32 v155, v155
	v_exp_f32_e32 v177, v177
	v_add_f32_e32 v172, 1.0, v172
	v_add_f32_e32 v173, 1.0, v173
	v_add_f32_e32 v174, 1.0, v174
	v_add_f32_e32 v176, 1.0, v176
	v_add_f32_e32 v175, 1.0, v175
	v_add_f32_e32 v142, 1.0, v142
	v_add_f32_e32 v155, 1.0, v155
	v_add_f32_e32 v177, 1.0, v177
	v_rcp_f32_e32 v172, v172
	v_rcp_f32_e32 v178, v173
	v_rcp_f32_e32 v173, v174
	v_rcp_f32_e32 v174, v175
	v_rcp_f32_e32 v175, v176
	v_rcp_f32_e32 v142, v142
	v_rcp_f32_e32 v155, v155
	v_rcp_f32_e32 v176, v177
	v_cvt_pk_bf16_f32 v172, v142, v172
	v_cvt_pk_bf16_f32 v173, v173, v174
	v_cvt_pk_bf16_f32 v174, v155, v178
	v_cvt_pk_bf16_f32 v175, v175, v176
	global_store_dwordx4 v[158:159], v[172:175], off
	v_add_f32_e32 v142, v116, v246
	v_add_f32_e32 v155, v112, v250
	v_add_f32_e32 v172, v117, v247
	v_add_f32_e32 v173, v113, v251
	v_add_f32_e32 v174, v118, v248
	v_add_f32_e32 v176, v114, v252
	v_add_f32_e32 v175, v119, v249
	v_add_f32_e32 v177, v115, v253
	v_mul_f32_e32 v172, 0xbfb8aa3b, v172
	v_mul_f32_e32 v173, 0xbfb8aa3b, v173
	v_mul_f32_e32 v174, 0xbfb8aa3b, v174
	v_mul_f32_e32 v176, 0xbfb8aa3b, v176
	v_mul_f32_e32 v175, 0xbfb8aa3b, v175
	v_mul_f32_e32 v142, 0xbfb8aa3b, v142
	v_mul_f32_e32 v155, 0xbfb8aa3b, v155
	v_mul_f32_e32 v177, 0xbfb8aa3b, v177
	v_exp_f32_e32 v172, v172
	v_exp_f32_e32 v173, v173
	v_exp_f32_e32 v174, v174
	v_exp_f32_e32 v176, v176
	v_exp_f32_e32 v175, v175
	v_exp_f32_e32 v142, v142
	v_exp_f32_e32 v155, v155
	v_exp_f32_e32 v177, v177
	v_add_f32_e32 v172, 1.0, v172
	v_add_f32_e32 v173, 1.0, v173
	v_add_f32_e32 v174, 1.0, v174
	v_add_f32_e32 v176, 1.0, v176
	v_add_f32_e32 v175, 1.0, v175
	v_add_f32_e32 v142, 1.0, v142
	v_add_f32_e32 v155, 1.0, v155
	v_add_f32_e32 v177, 1.0, v177
	v_rcp_f32_e32 v172, v172
	v_rcp_f32_e32 v178, v173
	v_rcp_f32_e32 v173, v174
	v_rcp_f32_e32 v174, v175
	v_rcp_f32_e32 v175, v176
	v_rcp_f32_e32 v142, v142
	v_rcp_f32_e32 v155, v155
	v_rcp_f32_e32 v176, v177
	v_cvt_pk_bf16_f32 v172, v142, v172
	v_cvt_pk_bf16_f32 v173, v173, v174
	v_cvt_pk_bf16_f32 v174, v155, v178
	v_cvt_pk_bf16_f32 v175, v175, v176
	global_store_dwordx4 v[158:159], v[172:175], off offset:256
	v_or_b32_e32 v158, 16, v154
	v_ashrrev_i32_e32 v159, 31, v158
	v_lshlrev_b64 v[158:159], 12, v[158:159]
	v_lshl_add_u64 v[158:159], s[12:13], 0, v[158:159]
	v_lshl_add_u64 v[158:159], v[158:159], 0, v[156:157]
	v_add_f32_e32 v142, v108, v238
	v_add_f32_e32 v155, v104, v242
	v_add_f32_e32 v172, v109, v239
	v_add_f32_e32 v173, v105, v243
	v_add_f32_e32 v174, v110, v240
	v_add_f32_e32 v176, v106, v244
	v_add_f32_e32 v175, v111, v241
	v_add_f32_e32 v177, v107, v245
	v_mul_f32_e32 v172, 0xbfb8aa3b, v172
	v_mul_f32_e32 v173, 0xbfb8aa3b, v173
	v_mul_f32_e32 v174, 0xbfb8aa3b, v174
	v_mul_f32_e32 v176, 0xbfb8aa3b, v176
	v_mul_f32_e32 v175, 0xbfb8aa3b, v175
	v_mul_f32_e32 v142, 0xbfb8aa3b, v142
	v_mul_f32_e32 v155, 0xbfb8aa3b, v155
	v_mul_f32_e32 v177, 0xbfb8aa3b, v177
	v_exp_f32_e32 v172, v172
	v_exp_f32_e32 v173, v173
	v_exp_f32_e32 v174, v174
	v_exp_f32_e32 v176, v176
	v_exp_f32_e32 v175, v175
	v_exp_f32_e32 v142, v142
	v_exp_f32_e32 v155, v155
	v_exp_f32_e32 v177, v177
	v_add_f32_e32 v172, 1.0, v172
	v_add_f32_e32 v173, 1.0, v173
	v_add_f32_e32 v174, 1.0, v174
	v_add_f32_e32 v176, 1.0, v176
	v_add_f32_e32 v175, 1.0, v175
	v_add_f32_e32 v142, 1.0, v142
	v_add_f32_e32 v155, 1.0, v155
	v_add_f32_e32 v177, 1.0, v177
	v_rcp_f32_e32 v172, v172
	v_rcp_f32_e32 v178, v173
	v_rcp_f32_e32 v173, v174
	v_rcp_f32_e32 v174, v175
	v_rcp_f32_e32 v175, v176
	v_rcp_f32_e32 v142, v142
	v_rcp_f32_e32 v155, v155
	v_rcp_f32_e32 v176, v177
	v_cvt_pk_bf16_f32 v172, v142, v172
	v_cvt_pk_bf16_f32 v173, v173, v174
	v_cvt_pk_bf16_f32 v174, v155, v178
	v_cvt_pk_bf16_f32 v175, v175, v176
	global_store_dwordx4 v[158:159], v[172:175], off
	v_add_f32_e32 v142, v100, v246
	v_add_f32_e32 v155, v96, v250
	v_add_f32_e32 v172, v101, v247
	v_add_f32_e32 v173, v97, v251
	v_add_f32_e32 v174, v102, v248
	v_add_f32_e32 v176, v98, v252
	v_add_f32_e32 v175, v103, v249
	v_add_f32_e32 v177, v99, v253
	v_mul_f32_e32 v172, 0xbfb8aa3b, v172
	v_mul_f32_e32 v173, 0xbfb8aa3b, v173
	v_mul_f32_e32 v174, 0xbfb8aa3b, v174
	v_mul_f32_e32 v176, 0xbfb8aa3b, v176
; __device__ __forceinline__ float fast_sigmoid(float z) { return __builtin_amdgcn_rcpf(1.f + __builtin_amdgcn_exp2f(-z * L2E)); }
; __device__ __forceinline__ u32x4 pack8(f32x4 a, f32x4 b) { u32x4 w; w.x = cvt_pk_bf16(a[0], a[1]); w.y = cvt_pk_bf16(a[2], a[3]); w.z = cvt_pk_bf16(b[0], b[1]); w.w = cvt_pk_bf16(b[2], b[3]); return w; }
; #define EPI_LOOP(...) _Pragma("unroll") for (int ai = 0; ai < 2; ++ai) _Pragma("unroll") for (int m = 0; m < 4; ++m) { const int row = u.pm * 256 + ai * 128 + wr * 64 + m * 16 + fr; \
;     _Pragma("unroll") for (int bj = 0; bj < 2; ++bj) { const int tc = bj * 128 + wc * 32 + 8 * fq; f32x4 v0 = acc[ai][bj][m][0], v1 = acc[ai][bj][m][1]; __VA_ARGS__ } }
;     __device__ __forceinline__ void operator()(const f32x4 (&acc)[2][2][4][2], const pg8::Unit& u, int wr, int wc, int fr, int fq) const {
;     ...
;             const int gt = (u.pn - 20) * 256;
;             EPI_LOOP({ const int col = gt + tc; const f32x4 b0 = *(const f32x4*)(b_gate + col), b1 = *(const f32x4*)(b_gate + col + 4);
;                        _Pragma("unroll") for (int i = 0; i < 4; ++i) { v0[i] = fast_sigmoid(v0[i] + b0[i]); v1[i] = fast_sigmoid(v1[i] + b1[i]); }
;                        *(u32x4*)(G + (size_t)row * 2048 + col) = pack8(v0, v1); })
	v_mul_f32_e32 v175, 0xbfb8aa3b, v175
	v_mul_f32_e32 v142, 0xbfb8aa3b, v142
	v_mul_f32_e32 v155, 0xbfb8aa3b, v155
	v_mul_f32_e32 v177, 0xbfb8aa3b, v177
	v_exp_f32_e32 v172, v172
	v_exp_f32_e32 v173, v173
	v_exp_f32_e32 v174, v174
	v_exp_f32_e32 v176, v176
	v_exp_f32_e32 v175, v175
	v_exp_f32_e32 v142, v142
	v_exp_f32_e32 v155, v155
	v_exp_f32_e32 v177, v177
	v_add_f32_e32 v172, 1.0, v172
	v_add_f32_e32 v173, 1.0, v173
	v_add_f32_e32 v174, 1.0, v174
	v_add_f32_e32 v176, 1.0, v176
	v_add_f32_e32 v175, 1.0, v175
	v_add_f32_e32 v142, 1.0, v142
	v_add_f32_e32 v155, 1.0, v155
	v_add_f32_e32 v177, 1.0, v177
	v_rcp_f32_e32 v172, v172
	v_rcp_f32_e32 v178, v173
	v_rcp_f32_e32 v173, v174
	v_rcp_f32_e32 v174, v175
	v_rcp_f32_e32 v175, v176
	v_rcp_f32_e32 v142, v142
	v_rcp_f32_e32 v155, v155
	v_rcp_f32_e32 v176, v177
	v_cvt_pk_bf16_f32 v172, v142, v172
	v_cvt_pk_bf16_f32 v173, v173, v174
	v_cvt_pk_bf16_f32 v174, v155, v178
	v_cvt_pk_bf16_f32 v175, v175, v176
	global_store_dwordx4 v[158:159], v[172:175], off offset:256
	v_or_b32_e32 v158, 32, v154
	v_ashrrev_i32_e32 v159, 31, v158
	v_lshlrev_b64 v[158:159], 12, v[158:159]
	v_lshl_add_u64 v[158:159], s[12:13], 0, v[158:159]
	v_lshl_add_u64 v[158:159], v[158:159], 0, v[156:157]
	v_add_f32_e32 v142, v92, v238
	v_add_f32_e32 v155, v88, v242
	v_add_f32_e32 v172, v93, v239
	v_add_f32_e32 v173, v89, v243
	v_add_f32_e32 v174, v94, v240
	v_add_f32_e32 v176, v90, v244
	v_add_f32_e32 v175, v95, v241
	v_add_f32_e32 v177, v91, v245
	v_mul_f32_e32 v172, 0xbfb8aa3b, v172
	v_mul_f32_e32 v173, 0xbfb8aa3b, v173
	v_mul_f32_e32 v174, 0xbfb8aa3b, v174
	v_mul_f32_e32 v176, 0xbfb8aa3b, v176
	v_mul_f32_e32 v175, 0xbfb8aa3b, v175
	v_mul_f32_e32 v142, 0xbfb8aa3b, v142
	v_mul_f32_e32 v155, 0xbfb8aa3b, v155
	v_mul_f32_e32 v177, 0xbfb8aa3b, v177
	v_exp_f32_e32 v172, v172
	v_exp_f32_e32 v173, v173
	v_exp_f32_e32 v174, v174
	v_exp_f32_e32 v176, v176
	v_exp_f32_e32 v175, v175
	v_exp_f32_e32 v142, v142
	v_exp_f32_e32 v155, v155
	v_exp_f32_e32 v177, v177
	v_add_f32_e32 v172, 1.0, v172
	v_add_f32_e32 v173, 1.0, v173
	v_add_f32_e32 v174, 1.0, v174
	v_add_f32_e32 v176, 1.0, v176
	v_add_f32_e32 v175, 1.0, v175
	v_add_f32_e32 v142, 1.0, v142
	v_add_f32_e32 v155, 1.0, v155
	v_add_f32_e32 v177, 1.0, v177
	v_rcp_f32_e32 v172, v172
	v_rcp_f32_e32 v178, v173
	v_rcp_f32_e32 v173, v174
	v_rcp_f32_e32 v174, v175
	v_rcp_f32_e32 v175, v176
	v_rcp_f32_e32 v142, v142
	v_rcp_f32_e32 v155, v155
	v_rcp_f32_e32 v176, v177
	v_cvt_pk_bf16_f32 v172, v142, v172
	v_cvt_pk_bf16_f32 v173, v173, v174
	v_cvt_pk_bf16_f32 v174, v155, v178
	v_cvt_pk_bf16_f32 v175, v175, v176
	global_store_dwordx4 v[158:159], v[172:175], off
	v_add_f32_e32 v142, v84, v246
	v_add_f32_e32 v155, v80, v250
	v_add_f32_e32 v172, v85, v247
	v_add_f32_e32 v173, v81, v251
	v_add_f32_e32 v174, v86, v248
	v_add_f32_e32 v176, v82, v252
	v_add_f32_e32 v175, v87, v249
	v_add_f32_e32 v177, v83, v253
	v_mul_f32_e32 v172, 0xbfb8aa3b, v172
	v_mul_f32_e32 v173, 0xbfb8aa3b, v173
	v_mul_f32_e32 v174, 0xbfb8aa3b, v174
	v_mul_f32_e32 v176, 0xbfb8aa3b, v176
	v_mul_f32_e32 v175, 0xbfb8aa3b, v175
	v_mul_f32_e32 v142, 0xbfb8aa3b, v142
	v_mul_f32_e32 v155, 0xbfb8aa3b, v155
	v_mul_f32_e32 v177, 0xbfb8aa3b, v177
	v_exp_f32_e32 v172, v172
	v_exp_f32_e32 v173, v173
	v_exp_f32_e32 v174, v174
	v_exp_f32_e32 v176, v176
	v_exp_f32_e32 v175, v175
	v_exp_f32_e32 v142, v142
	v_exp_f32_e32 v155, v155
	v_exp_f32_e32 v177, v177
	v_add_f32_e32 v172, 1.0, v172
	v_add_f32_e32 v173, 1.0, v173
	v_add_f32_e32 v174, 1.0, v174
	v_add_f32_e32 v176, 1.0, v176
	v_add_f32_e32 v175, 1.0, v175
	v_add_f32_e32 v142, 1.0, v142
	v_add_f32_e32 v155, 1.0, v155
	v_add_f32_e32 v177, 1.0, v177
	v_rcp_f32_e32 v172, v172
	v_rcp_f32_e32 v178, v173
	v_rcp_f32_e32 v173, v174
	v_rcp_f32_e32 v174, v175
	v_rcp_f32_e32 v175, v176
	v_rcp_f32_e32 v142, v142
	v_rcp_f32_e32 v155, v155
	v_rcp_f32_e32 v176, v177
	v_cvt_pk_bf16_f32 v172, v142, v172
	v_cvt_pk_bf16_f32 v173, v173, v174
	v_cvt_pk_bf16_f32 v174, v155, v178
	v_cvt_pk_bf16_f32 v175, v175, v176
	global_store_dwordx4 v[158:159], v[172:175], off offset:256
	v_or_b32_e32 v158, 48, v154
	v_ashrrev_i32_e32 v159, 31, v158
	v_lshlrev_b64 v[158:159], 12, v[158:159]
	v_lshl_add_u64 v[158:159], s[12:13], 0, v[158:159]
	v_lshl_add_u64 v[158:159], v[158:159], 0, v[156:157]
	v_add_f32_e32 v142, v76, v238
	v_add_f32_e32 v155, v72, v242
	v_add_f32_e32 v172, v77, v239
	v_add_f32_e32 v173, v73, v243
	v_add_f32_e32 v174, v78, v240
	v_add_f32_e32 v176, v74, v244
	v_add_f32_e32 v175, v79, v241
	v_add_f32_e32 v177, v75, v245
	v_mul_f32_e32 v172, 0xbfb8aa3b, v172
	v_mul_f32_e32 v173, 0xbfb8aa3b, v173
	v_mul_f32_e32 v174, 0xbfb8aa3b, v174
	v_mul_f32_e32 v176, 0xbfb8aa3b, v176
	v_mul_f32_e32 v175, 0xbfb8aa3b, v175
	v_mul_f32_e32 v142, 0xbfb8aa3b, v142
	v_mul_f32_e32 v155, 0xbfb8aa3b, v155
	v_mul_f32_e32 v177, 0xbfb8aa3b, v177
	v_exp_f32_e32 v172, v172
	v_exp_f32_e32 v173, v173
	v_exp_f32_e32 v174, v174
	v_exp_f32_e32 v176, v176
	v_exp_f32_e32 v175, v175
	v_exp_f32_e32 v142, v142
	v_exp_f32_e32 v155, v155
	v_exp_f32_e32 v177, v177
	v_add_f32_e32 v172, 1.0, v172
	v_add_f32_e32 v173, 1.0, v173
	v_add_f32_e32 v174, 1.0, v174
	v_add_f32_e32 v176, 1.0, v176
	v_add_f32_e32 v175, 1.0, v175
	v_add_f32_e32 v142, 1.0, v142
	v_add_f32_e32 v155, 1.0, v155
	v_add_f32_e32 v177, 1.0, v177
	v_rcp_f32_e32 v172, v172
	v_rcp_f32_e32 v178, v173
	v_rcp_f32_e32 v173, v174
	v_rcp_f32_e32 v174, v175
	v_rcp_f32_e32 v175, v176
	v_rcp_f32_e32 v142, v142
	v_rcp_f32_e32 v155, v155
	v_rcp_f32_e32 v176, v177
	v_cvt_pk_bf16_f32 v172, v142, v172
	v_cvt_pk_bf16_f32 v173, v173, v174
	v_cvt_pk_bf16_f32 v174, v155, v178
	v_cvt_pk_bf16_f32 v175, v175, v176
; __device__ __forceinline__ float fast_sigmoid(float z) { return __builtin_amdgcn_rcpf(1.f + __builtin_amdgcn_exp2f(-z * L2E)); }
; __device__ __forceinline__ u32x4 pack8(f32x4 a, f32x4 b) { u32x4 w; w.x = cvt_pk_bf16(a[0], a[1]); w.y = cvt_pk_bf16(a[2], a[3]); w.z = cvt_pk_bf16(b[0], b[1]); w.w = cvt_pk_bf16(b[2], b[3]); return w; }
; #define EPI_LOOP(...) _Pragma("unroll") for (int ai = 0; ai < 2; ++ai) _Pragma("unroll") for (int m = 0; m < 4; ++m) { const int row = u.pm * 256 + ai * 128 + wr * 64 + m * 16 + fr; \
;     _Pragma("unroll") for (int bj = 0; bj < 2; ++bj) { const int tc = bj * 128 + wc * 32 + 8 * fq; f32x4 v0 = acc[ai][bj][m][0], v1 = acc[ai][bj][m][1]; __VA_ARGS__ } }
;     __device__ __forceinline__ void operator()(const f32x4 (&acc)[2][2][4][2], const pg8::Unit& u, int wr, int wc, int fr, int fq) const {
;     ...
;             const int gt = (u.pn - 20) * 256;
;             EPI_LOOP({ const int col = gt + tc; const f32x4 b0 = *(const f32x4*)(b_gate + col), b1 = *(const f32x4*)(b_gate + col + 4);
;                        _Pragma("unroll") for (int i = 0; i < 4; ++i) { v0[i] = fast_sigmoid(v0[i] + b0[i]); v1[i] = fast_sigmoid(v1[i] + b1[i]); }
;                        *(u32x4*)(G + (size_t)row * 2048 + col) = pack8(v0, v1); })
	global_store_dwordx4 v[158:159], v[172:175], off
	v_add_f32_e32 v142, v68, v246
	v_add_f32_e32 v155, v64, v250
	v_add_f32_e32 v172, v69, v247
	v_add_f32_e32 v173, v65, v251
	v_add_f32_e32 v174, v70, v248
	v_add_f32_e32 v176, v66, v252
	v_add_f32_e32 v175, v71, v249
	v_add_f32_e32 v177, v67, v253
	v_mul_f32_e32 v172, 0xbfb8aa3b, v172
	v_mul_f32_e32 v173, 0xbfb8aa3b, v173
	v_mul_f32_e32 v174, 0xbfb8aa3b, v174
	v_mul_f32_e32 v176, 0xbfb8aa3b, v176
	v_mul_f32_e32 v175, 0xbfb8aa3b, v175
	v_mul_f32_e32 v142, 0xbfb8aa3b, v142
	v_mul_f32_e32 v155, 0xbfb8aa3b, v155
	v_mul_f32_e32 v177, 0xbfb8aa3b, v177
	v_exp_f32_e32 v172, v172
	v_exp_f32_e32 v173, v173
	v_exp_f32_e32 v174, v174
	v_exp_f32_e32 v176, v176
	v_exp_f32_e32 v175, v175
	v_exp_f32_e32 v142, v142
	v_exp_f32_e32 v155, v155
	v_exp_f32_e32 v177, v177
	v_add_f32_e32 v172, 1.0, v172
	v_add_f32_e32 v173, 1.0, v173
	v_add_f32_e32 v174, 1.0, v174
	v_add_f32_e32 v176, 1.0, v176
	v_add_f32_e32 v175, 1.0, v175
	v_add_f32_e32 v142, 1.0, v142
	v_add_f32_e32 v155, 1.0, v155
	v_add_f32_e32 v177, 1.0, v177
	v_rcp_f32_e32 v172, v172
	v_rcp_f32_e32 v178, v173
	v_rcp_f32_e32 v173, v174
	v_rcp_f32_e32 v174, v175
	v_rcp_f32_e32 v175, v176
	v_rcp_f32_e32 v142, v142
	v_rcp_f32_e32 v155, v155
	v_rcp_f32_e32 v176, v177
	v_cvt_pk_bf16_f32 v172, v142, v172
	v_cvt_pk_bf16_f32 v173, v173, v174
	v_cvt_pk_bf16_f32 v174, v155, v178
	v_cvt_pk_bf16_f32 v175, v175, v176
	global_store_dwordx4 v[158:159], v[172:175], off offset:256
	v_add_u32_e32 v158, 0x80, v154
	v_ashrrev_i32_e32 v159, 31, v158
	v_lshlrev_b64 v[158:159], 12, v[158:159]
	v_lshl_add_u64 v[158:159], s[12:13], 0, v[158:159]
	v_lshl_add_u64 v[158:159], v[158:159], 0, v[156:157]
	v_add_f32_e32 v142, v60, v238
	v_add_f32_e32 v155, v56, v242
	v_add_f32_e32 v172, v61, v239
	v_add_f32_e32 v173, v57, v243
	v_add_f32_e32 v174, v62, v240
	v_add_f32_e32 v176, v58, v244
	v_add_f32_e32 v175, v63, v241
	v_add_f32_e32 v177, v59, v245
	v_mul_f32_e32 v172, 0xbfb8aa3b, v172
	v_mul_f32_e32 v173, 0xbfb8aa3b, v173
	v_mul_f32_e32 v174, 0xbfb8aa3b, v174
	v_mul_f32_e32 v176, 0xbfb8aa3b, v176
	v_mul_f32_e32 v175, 0xbfb8aa3b, v175
	v_mul_f32_e32 v142, 0xbfb8aa3b, v142
	v_mul_f32_e32 v155, 0xbfb8aa3b, v155
	v_mul_f32_e32 v177, 0xbfb8aa3b, v177
	v_exp_f32_e32 v172, v172
	v_exp_f32_e32 v173, v173
	v_exp_f32_e32 v174, v174
	v_exp_f32_e32 v176, v176
	v_exp_f32_e32 v175, v175
	v_exp_f32_e32 v142, v142
	v_exp_f32_e32 v155, v155
	v_exp_f32_e32 v177, v177
	v_add_f32_e32 v172, 1.0, v172
	v_add_f32_e32 v173, 1.0, v173
	v_add_f32_e32 v174, 1.0, v174
	v_add_f32_e32 v176, 1.0, v176
	v_add_f32_e32 v175, 1.0, v175
	v_add_f32_e32 v142, 1.0, v142
	v_add_f32_e32 v155, 1.0, v155
	v_add_f32_e32 v177, 1.0, v177
	v_rcp_f32_e32 v172, v172
	v_rcp_f32_e32 v178, v173
	v_rcp_f32_e32 v173, v174
	v_rcp_f32_e32 v174, v175
	v_rcp_f32_e32 v175, v176
	v_rcp_f32_e32 v142, v142
	v_rcp_f32_e32 v155, v155
	v_rcp_f32_e32 v176, v177
	v_cvt_pk_bf16_f32 v172, v142, v172
	v_cvt_pk_bf16_f32 v173, v173, v174
	v_cvt_pk_bf16_f32 v174, v155, v178
	v_cvt_pk_bf16_f32 v175, v175, v176
	global_store_dwordx4 v[158:159], v[172:175], off
	v_add_f32_e32 v142, v52, v246
	v_add_f32_e32 v155, v48, v250
	v_add_f32_e32 v172, v53, v247
	v_add_f32_e32 v173, v49, v251
	v_add_f32_e32 v174, v54, v248
	v_add_f32_e32 v176, v50, v252
	v_add_f32_e32 v175, v55, v249
	v_add_f32_e32 v177, v51, v253
	v_mul_f32_e32 v172, 0xbfb8aa3b, v172
	v_mul_f32_e32 v173, 0xbfb8aa3b, v173
	v_mul_f32_e32 v174, 0xbfb8aa3b, v174
	v_mul_f32_e32 v176, 0xbfb8aa3b, v176
	v_mul_f32_e32 v175, 0xbfb8aa3b, v175
	v_mul_f32_e32 v142, 0xbfb8aa3b, v142
	v_mul_f32_e32 v155, 0xbfb8aa3b, v155
	v_mul_f32_e32 v177, 0xbfb8aa3b, v177
	v_exp_f32_e32 v172, v172
	v_exp_f32_e32 v173, v173
	v_exp_f32_e32 v174, v174
	v_exp_f32_e32 v176, v176
	v_exp_f32_e32 v175, v175
	v_exp_f32_e32 v142, v142
	v_exp_f32_e32 v155, v155
	v_exp_f32_e32 v177, v177
	v_add_f32_e32 v172, 1.0, v172
	v_add_f32_e32 v173, 1.0, v173
	v_add_f32_e32 v174, 1.0, v174
	v_add_f32_e32 v176, 1.0, v176
	v_add_f32_e32 v175, 1.0, v175
	v_add_f32_e32 v142, 1.0, v142
	v_add_f32_e32 v155, 1.0, v155
	v_add_f32_e32 v177, 1.0, v177
	v_rcp_f32_e32 v172, v172
	v_rcp_f32_e32 v178, v173
	v_rcp_f32_e32 v173, v174
	v_rcp_f32_e32 v174, v175
	v_rcp_f32_e32 v175, v176
	v_rcp_f32_e32 v142, v142
	v_rcp_f32_e32 v155, v155
	v_rcp_f32_e32 v176, v177
	v_cvt_pk_bf16_f32 v172, v142, v172
	v_cvt_pk_bf16_f32 v173, v173, v174
	v_cvt_pk_bf16_f32 v174, v155, v178
	v_cvt_pk_bf16_f32 v175, v175, v176
	global_store_dwordx4 v[158:159], v[172:175], off offset:256
	v_add_u32_e32 v158, 0x90, v154
	v_ashrrev_i32_e32 v159, 31, v158
	v_lshlrev_b64 v[158:159], 12, v[158:159]
	v_lshl_add_u64 v[158:159], s[12:13], 0, v[158:159]
	v_lshl_add_u64 v[158:159], v[158:159], 0, v[156:157]
	v_add_f32_e32 v142, v44, v238
	v_add_f32_e32 v155, v40, v242
	v_add_f32_e32 v172, v45, v239
	v_add_f32_e32 v173, v41, v243
	v_add_f32_e32 v174, v46, v240
	v_add_f32_e32 v176, v42, v244
	v_add_f32_e32 v175, v47, v241
	v_add_f32_e32 v177, v43, v245
	v_mul_f32_e32 v172, 0xbfb8aa3b, v172
	v_mul_f32_e32 v173, 0xbfb8aa3b, v173
	v_mul_f32_e32 v174, 0xbfb8aa3b, v174
	v_mul_f32_e32 v176, 0xbfb8aa3b, v176
	v_mul_f32_e32 v175, 0xbfb8aa3b, v175
	v_mul_f32_e32 v142, 0xbfb8aa3b, v142
	v_mul_f32_e32 v155, 0xbfb8aa3b, v155
	v_mul_f32_e32 v177, 0xbfb8aa3b, v177
	v_exp_f32_e32 v172, v172
	v_exp_f32_e32 v173, v173
	v_exp_f32_e32 v174, v174
	v_exp_f32_e32 v176, v176
	v_exp_f32_e32 v175, v175
	v_exp_f32_e32 v142, v142
	v_exp_f32_e32 v155, v155
	v_exp_f32_e32 v177, v177
	v_add_f32_e32 v172, 1.0, v172
	v_add_f32_e32 v173, 1.0, v173
	v_add_f32_e32 v174, 1.0, v174
	v_add_f32_e32 v176, 1.0, v176
	v_add_f32_e32 v175, 1.0, v175
; __device__ __forceinline__ float fast_sigmoid(float z) { return __builtin_amdgcn_rcpf(1.f + __builtin_amdgcn_exp2f(-z * L2E)); }
; __device__ __forceinline__ u32x4 pack8(f32x4 a, f32x4 b) { u32x4 w; w.x = cvt_pk_bf16(a[0], a[1]); w.y = cvt_pk_bf16(a[2], a[3]); w.z = cvt_pk_bf16(b[0], b[1]); w.w = cvt_pk_bf16(b[2], b[3]); return w; }
; #define EPI_LOOP(...) _Pragma("unroll") for (int ai = 0; ai < 2; ++ai) _Pragma("unroll") for (int m = 0; m < 4; ++m) { const int row = u.pm * 256 + ai * 128 + wr * 64 + m * 16 + fr; \
;     _Pragma("unroll") for (int bj = 0; bj < 2; ++bj) { const int tc = bj * 128 + wc * 32 + 8 * fq; f32x4 v0 = acc[ai][bj][m][0], v1 = acc[ai][bj][m][1]; __VA_ARGS__ } }
;     __device__ __forceinline__ void operator()(const f32x4 (&acc)[2][2][4][2], const pg8::Unit& u, int wr, int wc, int fr, int fq) const {
;     ...
;             const int gt = (u.pn - 20) * 256;
;             EPI_LOOP({ const int col = gt + tc; const f32x4 b0 = *(const f32x4*)(b_gate + col), b1 = *(const f32x4*)(b_gate + col + 4);
;                        _Pragma("unroll") for (int i = 0; i < 4; ++i) { v0[i] = fast_sigmoid(v0[i] + b0[i]); v1[i] = fast_sigmoid(v1[i] + b1[i]); }
;                        *(u32x4*)(G + (size_t)row * 2048 + col) = pack8(v0, v1); })
	v_add_f32_e32 v142, 1.0, v142
	v_add_f32_e32 v155, 1.0, v155
	v_add_f32_e32 v177, 1.0, v177
	v_rcp_f32_e32 v172, v172
	v_rcp_f32_e32 v178, v173
	v_rcp_f32_e32 v173, v174
	v_rcp_f32_e32 v174, v175
	v_rcp_f32_e32 v175, v176
	v_rcp_f32_e32 v142, v142
	v_rcp_f32_e32 v155, v155
	v_rcp_f32_e32 v176, v177
	v_cvt_pk_bf16_f32 v172, v142, v172
	v_cvt_pk_bf16_f32 v173, v173, v174
	v_cvt_pk_bf16_f32 v174, v155, v178
	v_cvt_pk_bf16_f32 v175, v175, v176
	global_store_dwordx4 v[158:159], v[172:175], off
	v_add_f32_e32 v142, v36, v246
	v_add_f32_e32 v155, v32, v250
	v_add_f32_e32 v172, v37, v247
	v_add_f32_e32 v173, v33, v251
	v_add_f32_e32 v174, v38, v248
	v_add_f32_e32 v176, v34, v252
	v_add_f32_e32 v175, v39, v249
	v_add_f32_e32 v177, v35, v253
	v_mul_f32_e32 v172, 0xbfb8aa3b, v172
	v_mul_f32_e32 v173, 0xbfb8aa3b, v173
	v_mul_f32_e32 v174, 0xbfb8aa3b, v174
	v_mul_f32_e32 v176, 0xbfb8aa3b, v176
	v_mul_f32_e32 v175, 0xbfb8aa3b, v175
	v_mul_f32_e32 v142, 0xbfb8aa3b, v142
	v_mul_f32_e32 v155, 0xbfb8aa3b, v155
	v_mul_f32_e32 v177, 0xbfb8aa3b, v177
	v_exp_f32_e32 v172, v172
	v_exp_f32_e32 v173, v173
	v_exp_f32_e32 v174, v174
	v_exp_f32_e32 v176, v176
	v_exp_f32_e32 v175, v175
	v_exp_f32_e32 v142, v142
	v_exp_f32_e32 v155, v155
	v_exp_f32_e32 v177, v177
	v_add_f32_e32 v172, 1.0, v172
	v_add_f32_e32 v173, 1.0, v173
	v_add_f32_e32 v174, 1.0, v174
	v_add_f32_e32 v176, 1.0, v176
	v_add_f32_e32 v175, 1.0, v175
	v_add_f32_e32 v142, 1.0, v142
	v_add_f32_e32 v155, 1.0, v155
	v_add_f32_e32 v177, 1.0, v177
	v_rcp_f32_e32 v172, v172
	v_rcp_f32_e32 v178, v173
	v_rcp_f32_e32 v173, v174
	v_rcp_f32_e32 v174, v175
	v_rcp_f32_e32 v175, v176
	v_rcp_f32_e32 v142, v142
	v_rcp_f32_e32 v155, v155
	v_rcp_f32_e32 v176, v177
	v_cvt_pk_bf16_f32 v172, v142, v172
	v_cvt_pk_bf16_f32 v173, v173, v174
	v_cvt_pk_bf16_f32 v174, v155, v178
	v_cvt_pk_bf16_f32 v175, v175, v176
	global_store_dwordx4 v[158:159], v[172:175], off offset:256
	v_add_u32_e32 v158, 0xa0, v154
	v_ashrrev_i32_e32 v159, 31, v158
	v_lshlrev_b64 v[158:159], 12, v[158:159]
	v_lshl_add_u64 v[158:159], s[12:13], 0, v[158:159]
	v_lshl_add_u64 v[158:159], v[158:159], 0, v[156:157]
	v_add_u32_e32 v154, 0xb0, v154
	v_add_f32_e32 v142, v28, v238
	v_add_f32_e32 v155, v24, v242
	v_add_f32_e32 v172, v29, v239
	v_add_f32_e32 v173, v25, v243
	v_add_f32_e32 v174, v30, v240
	v_add_f32_e32 v176, v26, v244
	v_add_f32_e32 v175, v31, v241
	v_add_f32_e32 v177, v27, v245
	v_mul_f32_e32 v172, 0xbfb8aa3b, v172
	v_mul_f32_e32 v173, 0xbfb8aa3b, v173
	v_mul_f32_e32 v174, 0xbfb8aa3b, v174
	v_mul_f32_e32 v176, 0xbfb8aa3b, v176
	v_mul_f32_e32 v175, 0xbfb8aa3b, v175
	v_mul_f32_e32 v142, 0xbfb8aa3b, v142
	v_mul_f32_e32 v155, 0xbfb8aa3b, v155
	v_mul_f32_e32 v177, 0xbfb8aa3b, v177
	v_exp_f32_e32 v172, v172
	v_exp_f32_e32 v173, v173
	v_exp_f32_e32 v174, v174
	v_exp_f32_e32 v176, v176
	v_exp_f32_e32 v175, v175
	v_exp_f32_e32 v142, v142
	v_exp_f32_e32 v155, v155
	v_exp_f32_e32 v177, v177
	v_add_f32_e32 v172, 1.0, v172
	v_add_f32_e32 v173, 1.0, v173
	v_add_f32_e32 v174, 1.0, v174
	v_add_f32_e32 v176, 1.0, v176
	v_add_f32_e32 v175, 1.0, v175
	v_add_f32_e32 v142, 1.0, v142
	v_add_f32_e32 v155, 1.0, v155
	v_add_f32_e32 v177, 1.0, v177
	v_rcp_f32_e32 v172, v172
	v_rcp_f32_e32 v178, v173
	v_rcp_f32_e32 v173, v174
	v_rcp_f32_e32 v174, v175
	v_rcp_f32_e32 v175, v176
	v_rcp_f32_e32 v142, v142
	v_rcp_f32_e32 v155, v155
	v_rcp_f32_e32 v176, v177
	v_cvt_pk_bf16_f32 v172, v142, v172
	v_cvt_pk_bf16_f32 v173, v173, v174
	v_cvt_pk_bf16_f32 v174, v155, v178
	v_cvt_pk_bf16_f32 v175, v175, v176
	global_store_dwordx4 v[158:159], v[172:175], off
	v_add_f32_e32 v142, v20, v246
	v_add_f32_e32 v155, v16, v250
	v_add_f32_e32 v172, v21, v247
	v_add_f32_e32 v173, v17, v251
	v_add_f32_e32 v174, v22, v248
	v_add_f32_e32 v176, v18, v252
	v_add_f32_e32 v175, v23, v249
	v_add_f32_e32 v177, v19, v253
	v_mul_f32_e32 v172, 0xbfb8aa3b, v172
	v_mul_f32_e32 v173, 0xbfb8aa3b, v173
	v_mul_f32_e32 v174, 0xbfb8aa3b, v174
	v_mul_f32_e32 v176, 0xbfb8aa3b, v176
	v_mul_f32_e32 v175, 0xbfb8aa3b, v175
; __device__ __forceinline__ float fast_sigmoid(float z) { return __builtin_amdgcn_rcpf(1.f + __builtin_amdgcn_exp2f(-z * L2E)); }
; __device__ __forceinline__ u32x4 pack8(f32x4 a, f32x4 b) { u32x4 w; w.x = cvt_pk_bf16(a[0], a[1]); w.y = cvt_pk_bf16(a[2], a[3]); w.z = cvt_pk_bf16(b[0], b[1]); w.w = cvt_pk_bf16(b[2], b[3]); return w; }
; #define EPI_LOOP(...) _Pragma("unroll") for (int ai = 0; ai < 2; ++ai) _Pragma("unroll") for (int m = 0; m < 4; ++m) { const int row = u.pm * 256 + ai * 128 + wr * 64 + m * 16 + fr; \
;     _Pragma("unroll") for (int bj = 0; bj < 2; ++bj) { const int tc = bj * 128 + wc * 32 + 8 * fq; f32x4 v0 = acc[ai][bj][m][0], v1 = acc[ai][bj][m][1]; __VA_ARGS__ } }
;     __device__ __forceinline__ void operator()(const f32x4 (&acc)[2][2][4][2], const pg8::Unit& u, int wr, int wc, int fr, int fq) const {
;     ...
;             const int gt = (u.pn - 20) * 256;
;             EPI_LOOP({ const int col = gt + tc; const f32x4 b0 = *(const f32x4*)(b_gate + col), b1 = *(const f32x4*)(b_gate + col + 4);
;                        _Pragma("unroll") for (int i = 0; i < 4; ++i) { v0[i] = fast_sigmoid(v0[i] + b0[i]); v1[i] = fast_sigmoid(v1[i] + b1[i]); }
;                        *(u32x4*)(G + (size_t)row * 2048 + col) = pack8(v0, v1); })
	v_mul_f32_e32 v142, 0xbfb8aa3b, v142
	v_mul_f32_e32 v155, 0xbfb8aa3b, v155
	v_mul_f32_e32 v177, 0xbfb8aa3b, v177
	v_exp_f32_e32 v172, v172
	v_exp_f32_e32 v173, v173
	v_exp_f32_e32 v174, v174
	v_exp_f32_e32 v176, v176
	v_exp_f32_e32 v175, v175
	v_exp_f32_e32 v142, v142
	v_exp_f32_e32 v155, v155
	v_exp_f32_e32 v177, v177
	v_add_f32_e32 v172, 1.0, v172
	v_add_f32_e32 v173, 1.0, v173
	v_add_f32_e32 v174, 1.0, v174
	v_add_f32_e32 v176, 1.0, v176
	v_add_f32_e32 v175, 1.0, v175
	v_add_f32_e32 v142, 1.0, v142
	v_add_f32_e32 v155, 1.0, v155
	v_add_f32_e32 v177, 1.0, v177
	v_rcp_f32_e32 v172, v172
	v_rcp_f32_e32 v178, v173
	v_rcp_f32_e32 v173, v174
	v_rcp_f32_e32 v174, v175
	v_rcp_f32_e32 v175, v176
	v_rcp_f32_e32 v142, v142
	v_rcp_f32_e32 v155, v155
	v_rcp_f32_e32 v176, v177
	v_cvt_pk_bf16_f32 v172, v142, v172
	v_cvt_pk_bf16_f32 v173, v173, v174
	v_cvt_pk_bf16_f32 v174, v155, v178
	v_cvt_pk_bf16_f32 v175, v175, v176
	global_store_dwordx4 v[158:159], v[172:175], off offset:256
	v_ashrrev_i32_e32 v155, 31, v154
	v_lshlrev_b64 v[154:155], 12, v[154:155]
	v_lshl_add_u64 v[154:155], s[12:13], 0, v[154:155]
	v_lshl_add_u64 v[158:159], v[154:155], 0, v[156:157]
	v_add_f32_e32 v155, v13, v239
	v_add_f32_e32 v154, v8, v242
	v_add_f32_e32 v156, v9, v243
	v_add_f32_e32 v157, v14, v240
	v_add_f32_e32 v173, v15, v241
	v_add_f32_e32 v142, v12, v238
	v_add_f32_e32 v172, v10, v244
	v_add_f32_e32 v174, v11, v245
	v_mul_f32_e32 v154, 0xbfb8aa3b, v154
	v_mul_f32_e32 v155, 0xbfb8aa3b, v155
	v_mul_f32_e32 v156, 0xbfb8aa3b, v156
	v_mul_f32_e32 v157, 0xbfb8aa3b, v157
	v_mul_f32_e32 v173, 0xbfb8aa3b, v173
	v_mul_f32_e32 v142, 0xbfb8aa3b, v142
	v_mul_f32_e32 v172, 0xbfb8aa3b, v172
	v_mul_f32_e32 v174, 0xbfb8aa3b, v174
	v_exp_f32_e32 v154, v154
	v_exp_f32_e32 v155, v155
	v_exp_f32_e32 v156, v156
	v_exp_f32_e32 v157, v157
	v_exp_f32_e32 v173, v173
	v_exp_f32_e32 v142, v142
	v_exp_f32_e32 v172, v172
	v_exp_f32_e32 v174, v174
	v_add_f32_e32 v154, 1.0, v154
	v_add_f32_e32 v155, 1.0, v155
	v_add_f32_e32 v156, 1.0, v156
	v_add_f32_e32 v157, 1.0, v157
	v_add_f32_e32 v173, 1.0, v173
	v_add_f32_e32 v142, 1.0, v142
	v_add_f32_e32 v172, 1.0, v172
	v_add_f32_e32 v174, 1.0, v174
	v_rcp_f32_e32 v175, v154
	v_rcp_f32_e32 v154, v155
	v_rcp_f32_e32 v156, v156
	v_rcp_f32_e32 v155, v157
	v_rcp_f32_e32 v157, v173
	v_rcp_f32_e32 v142, v142
	v_rcp_f32_e32 v172, v172
	v_rcp_f32_e32 v173, v174
	v_cvt_pk_bf16_f32 v154, v142, v154
	v_cvt_pk_bf16_f32 v155, v155, v157
	v_cvt_pk_bf16_f32 v156, v175, v156
	v_cvt_pk_bf16_f32 v157, v172, v173
	global_store_dwordx4 v[158:159], v[154:157], off
	v_add_f32_e32 v142, v4, v246
	v_add_f32_e32 v152, v0, v250
	v_add_f32_e32 v153, v5, v247
	v_add_f32_e32 v154, v1, v251
	v_add_f32_e32 v155, v6, v248
	v_add_f32_e32 v157, v7, v249
	v_add_f32_e32 v156, v2, v252
	v_add_f32_e32 v172, v3, v253
	v_mul_f32_e32 v152, 0xbfb8aa3b, v152
	v_mul_f32_e32 v153, 0xbfb8aa3b, v153
	v_mul_f32_e32 v154, 0xbfb8aa3b, v154
	v_mul_f32_e32 v155, 0xbfb8aa3b, v155
	v_mul_f32_e32 v157, 0xbfb8aa3b, v157
	v_mul_f32_e32 v142, 0xbfb8aa3b, v142
	v_mul_f32_e32 v156, 0xbfb8aa3b, v156
	v_mul_f32_e32 v172, 0xbfb8aa3b, v172
	v_exp_f32_e32 v152, v152
	v_exp_f32_e32 v153, v153
	v_exp_f32_e32 v154, v154
	v_exp_f32_e32 v155, v155
	v_exp_f32_e32 v157, v157
	v_exp_f32_e32 v142, v142
	v_exp_f32_e32 v156, v156
	v_exp_f32_e32 v172, v172
	v_add_f32_e32 v152, 1.0, v152
	v_add_f32_e32 v153, 1.0, v153
	v_add_f32_e32 v154, 1.0, v154
	v_add_f32_e32 v155, 1.0, v155
	v_add_f32_e32 v157, 1.0, v157
	v_add_f32_e32 v142, 1.0, v142
	v_add_f32_e32 v156, 1.0, v156
	v_add_f32_e32 v172, 1.0, v172
	v_rcp_f32_e32 v173, v152
	v_rcp_f32_e32 v152, v153
	v_rcp_f32_e32 v154, v154
	v_rcp_f32_e32 v153, v155
	v_rcp_f32_e32 v155, v157
	v_rcp_f32_e32 v142, v142
	v_rcp_f32_e32 v156, v156
	v_rcp_f32_e32 v157, v172
	v_cvt_pk_bf16_f32 v152, v142, v152
	v_cvt_pk_bf16_f32 v153, v153, v155
	v_cvt_pk_bf16_f32 v154, v173, v154
	v_cvt_pk_bf16_f32 v155, v156, v157
	global_store_dwordx4 v[158:159], v[152:155], off offset:256
